# mixer-A tile loop: first QK fragment reads issued right after the barrier from addresses precomputed under the previous tile's PV2 MFMAs
# baseline (speedup 1.0000x reference)
.Lattn_prio_skip_a:
	s_mov_b32 s7, 0
	v_mbcnt_lo_u32_b32 v168, -1, 0
	v_mbcnt_hi_u32_b32 v168, -1, v168
	v_ashrrev_i32_e32 v169, 5, v168
	v_lshlrev_b32_e32 v170, 7, v168
	v_lshrrev_b32_e32 v171, 1, v168
	v_and_b32_e32 v170, 0xf80, v170
	v_bitop3_b32 v172, v171, v169, 7 bitop3:0x6c
	v_lshl_add_u32 v172, v172, 4, v170
	v_add_u32_e32 v173, 2, v169
	v_bitop3_b32 v173, v173, v171, 7 bitop3:0x78
	v_lshl_add_u32 v173, v173, 4, v170
	v_add_u32_e32 v160, s7, v172
	v_add_u32_e32 v203, s48, v172
	v_add_u32_e32 v205, s7, v173
	v_add_u32_e32 v252, s48, v173
	.p2align 5
	s_nop 0
	s_nop 0
	s_nop 0
	s_nop 0
	s_nop 0
	s_nop 0
	s_nop 0

.LBB0_407:
	ds_read_b128 v[128:131], v160
	ds_read_b128 v[132:135], v203
	ds_read_b128 v[136:139], v205
	ds_read_b128 v[140:143], v252
	v_mbcnt_lo_u32_b32 v208, -1, 0
	v_mbcnt_hi_u32_b32 v208, -1, v208
	s_add_i32 s7, s7, 0
	v_bfe_u32 v209, v208, 2, 2
	v_lshrrev_b32_e32 v210, 3, v208
	v_bfe_u32 v212, v208, 1, 1
	v_and_or_b32 v211, v210, s64, v209
	v_and_or_b32 v210, v210, 2, v212
	v_lshlrev_b32_e32 v208, 3, v208
	v_lshlrev_b32_e32 v211, 8, v211
	v_lshlrev_b32_e32 v210, 4, v210
	v_and_b32_e32 v208, 8, v208
	v_or3_b32 v160, v210, v211, v208
	v_lshlrev_b32_e32 v162, 6, v209
	v_mbcnt_lo_u32_b32 v208, -1, 0
	v_mbcnt_hi_u32_b32 v208, -1, v208
	v_or_b32_e32 v163, v160, v162
	v_ashrrev_i32_e32 v209, 5, v208
	v_lshlrev_b32_e32 v210, 7, v208
	v_lshrrev_b32_e32 v213, 1, v208
	v_and_b32_e32 v212, 0xf80, v210
	v_bitop3_b32 v208, v213, v209, 7 bitop3:0x6c
	v_lshl_add_u32 v214, v208, 4, v212
	v_add_u32_e32 v208, 2, v209
	v_bitop3_b32 v208, v208, v213, 7 bitop3:0x78
	v_lshl_add_u32 v216, v208, 4, v212
	v_add_u32_e32 v208, 4, v209
	v_bitop3_b32 v208, v208, v213, 7 bitop3:0x78
	v_add_u32_e32 v207, s7, v214
	v_lshl_add_u32 v168, v208, 4, v212
	v_add_u32_e32 v215, 6, v209
	v_bitop3_b32 v213, v215, v213, 7 bitop3:0x78
	v_add_u32_e32 v224, s48, v214
	v_add_u32_e32 v225, s7, v216
	v_lshl_add_u32 v169, v213, 4, v212
	v_add_u32_e32 v226, s48, v216
	v_bitop3_b32 v203, v160, s37, v162 bitop3:0x36
	v_bitop3_b32 v206, v160, s41, v162 bitop3:0x36
	s_waitcnt lgkmcnt(2)
	v_mfma_f32_32x32x16_bf16 v[144:159], v[128:131], v[132:135], 0
	v_add_u32_e32 v227, s7, v168
	v_add_u32_e32 v228, s48, v168
	ds_read_b128 v[128:131], v227
	ds_read_b128 v[132:135], v228
	s_waitcnt lgkmcnt(2)
	v_mfma_f32_32x32x16_bf16 v[144:159], v[136:139], v[140:143], v[144:159]
	v_add_u32_e32 v230, s7, v169
	v_add_u32_e32 v232, s48, v169
	ds_read_b128 v[136:139], v230
	ds_read_b128 v[140:143], v232
	s_waitcnt lgkmcnt(2)
	v_mfma_f32_32x32x16_bf16 v[144:159], v[128:131], v[132:135], v[144:159]
	ds_read_b128 v[128:131], v207 offset:8192
	ds_read_b128 v[132:135], v224 offset:4096
	s_waitcnt lgkmcnt(2)
	v_mfma_f32_32x32x16_bf16 v[144:159], v[136:139], v[140:143], v[144:159]
	ds_read_b128 v[178:181], v225 offset:8192
	ds_read_b128 v[182:185], v226 offset:4096
	s_waitcnt lgkmcnt(2)
	v_mfma_f32_32x32x16_bf16 v[128:143], v[128:131], v[132:135], 0
	s_nop 7
	v_exp_f32_e32 v173, v144
	v_exp_f32_e32 v169, v145
	v_exp_f32_e32 v177, v146
	v_exp_f32_e32 v171, v147
	ds_read_b128 v[144:147], v227 offset:8192
	ds_read_b128 v[190:193], v228 offset:4096
	s_waitcnt lgkmcnt(2)
	v_mfma_f32_32x32x16_bf16 v[128:143], v[178:181], v[182:185], v[128:143]
	v_exp_f32_e32 v183, v148
	v_exp_f32_e32 v175, v149
	v_exp_f32_e32 v189, v150
	v_exp_f32_e32 v179, v151
	ds_read_b128 v[148:151], v230 offset:8192
	ds_read_b128 v[196:199], v232 offset:4096
	s_waitcnt lgkmcnt(2)
	v_mfma_f32_32x32x16_bf16 v[128:143], v[144:147], v[190:193], v[128:143]
	v_exp_f32_e32 v193, v152
	v_exp_f32_e32 v181, v153
	v_exp_f32_e32 v195, v154
	v_exp_f32_e32 v187, v155
	s_waitcnt lgkmcnt(0)
	v_mfma_f32_32x32x16_bf16 v[128:143], v[148:151], v[196:199], v[128:143]
	v_exp_f32_e32 v197, v156
	v_exp_f32_e32 v185, v157
	v_exp_f32_e32 v199, v158
	v_exp_f32_e32 v191, v159
	s_cmp_eq_u32 s4, 0x3f0000
	s_cbranch_scc1 .Lattn_nodma_a
	v_mov_b32_e32 v213, 0
	v_add_u32_e32 v212, s4, v202
	s_xor_b32 s8, s7, 0x4000
	v_lshl_add_u64 v[208:209], v[212:213], 1, s[66:67]
	s_add_i32 s9, s49, s8
	s_mov_b32 s10, m0
	s_mov_b32 m0, s9
	s_nop 0
	global_load_lds_dwordx4 v[208:209], off
	s_mov_b32 m0, s10
	v_add_u32_e32 v210, s4, v201
	v_lshl_add_u64 v[208:209], v[208:209], 0, s[38:39]
	s_add_i32 s9, s33, s8
	s_mov_b32 s10, m0
	s_mov_b32 m0, s9
	s_nop 0
	global_load_lds_dwordx4 v[208:209], off
	s_mov_b32 m0, s10
	v_add_u32_e32 v212, 0x10000, v210
	v_lshl_add_u64 v[208:209], v[212:213], 1, s[68:69]
	s_add_i32 s9, s54, s8
	s_mov_b32 s10, m0
	s_mov_b32 m0, s9
	s_nop 0
	global_load_lds_dwordx4 v[208:209], off
	s_mov_b32 m0, s10
	v_add_u32_e32 v212, 0x18000, v210
	v_lshl_add_u64 v[208:209], v[212:213], 1, s[68:69]
	s_add_i32 s8, s47, s8
	s_mov_b32 s9, m0
	s_mov_b32 m0, s8
	s_nop 0
	global_load_lds_dwordx4 v[208:209], off
	s_mov_b32 m0, s9
.Lattn_dma_done_a:
	v_exp_f32_e32 v172, v128
	v_exp_f32_e32 v170, v129
	v_exp_f32_e32 v176, v130
	v_exp_f32_e32 v168, v131
	v_exp_f32_e32 v182, v132
	v_exp_f32_e32 v178, v133
	v_exp_f32_e32 v188, v134
	v_exp_f32_e32 v174, v135
	v_exp_f32_e32 v192, v136
	v_exp_f32_e32 v186, v137
	v_exp_f32_e32 v194, v138
	v_exp_f32_e32 v180, v139
	v_exp_f32_e32 v196, v140
	v_exp_f32_e32 v190, v141
	v_exp_f32_e32 v198, v142
	v_exp_f32_e32 v184, v143
	v_cvt_pk_bf16_f32 v144, v173, v169
	v_cvt_pk_bf16_f32 v145, v177, v171
	v_cvt_pk_bf16_f32 v146, v183, v175
	v_cvt_pk_bf16_f32 v147, v189, v179
	v_cvt_pk_bf16_f32 v148, v193, v181
	v_cvt_pk_bf16_f32 v149, v195, v187
	v_cvt_pk_bf16_f32 v150, v197, v185
	v_cvt_pk_bf16_f32 v151, v199, v191
	v_cvt_pk_bf16_f32 v128, v172, v170
	v_cvt_pk_bf16_f32 v129, v176, v168
	v_cvt_pk_bf16_f32 v130, v182, v178
	v_cvt_pk_bf16_f32 v131, v188, v174
	v_cvt_pk_bf16_f32 v132, v192, v186
	v_cvt_pk_bf16_f32 v133, v194, v180
	v_cvt_pk_bf16_f32 v134, v196, v190
	v_cvt_pk_bf16_f32 v135, v198, v184
	v_add3_u32 v160, s7, v162, v160
	v_xad_u32 v252, v163, 64, s7
	v_add_u32_e32 v203, s7, v203
	v_add_u32_e32 v205, s7, v206
	ds_read_b64_tr_b16 v[136:137], v160 offset:32768
	ds_read_b64_tr_b16 v[138:139], v160 offset:34816
	ds_read_b64_tr_b16 v[140:141], v160 offset:36864
	ds_read_b64_tr_b16 v[142:143], v160 offset:38912
	ds_read_b64_tr_b16 v[152:153], v252 offset:32768
	ds_read_b64_tr_b16 v[154:155], v252 offset:34816
	ds_read_b64_tr_b16 v[156:157], v252 offset:36864
	ds_read_b64_tr_b16 v[158:159], v252 offset:38912
	ds_read_b64_tr_b16 v[208:209], v203 offset:32768
	ds_read_b64_tr_b16 v[210:211], v203 offset:34816
	ds_read_b64_tr_b16 v[212:213], v203 offset:36864
	ds_read_b64_tr_b16 v[214:215], v203 offset:38912
	ds_read_b64_tr_b16 v[216:217], v205 offset:32768
	ds_read_b64_tr_b16 v[218:219], v205 offset:34816
	ds_read_b64_tr_b16 v[220:221], v205 offset:36864
	ds_read_b64_tr_b16 v[222:223], v205 offset:38912
	s_waitcnt lgkmcnt(14)
	v_mfma_f32_32x32x16_bf16 v[64:79], v[144:147], v[136:139], v[64:79]
	v_mfma_f32_32x32x16_bf16 v[0:15], v[128:131], v[136:139], v[0:15]
	s_waitcnt lgkmcnt(10)
	v_mfma_f32_32x32x16_bf16 v[80:95], v[144:147], v[152:155], v[80:95]
	v_mfma_f32_32x32x16_bf16 v[16:31], v[128:131], v[152:155], v[16:31]
	s_waitcnt lgkmcnt(6)
	v_mfma_f32_32x32x16_bf16 v[96:111], v[144:147], v[208:211], v[96:111]
	v_mfma_f32_32x32x16_bf16 v[32:47], v[128:131], v[208:211], v[32:47]
	s_waitcnt lgkmcnt(2)
	v_mfma_f32_32x32x16_bf16 v[112:127], v[144:147], v[216:219], v[112:127]
	v_mfma_f32_32x32x16_bf16 v[48:63], v[128:131], v[216:219], v[48:63]
	v_mfma_f32_32x32x16_bf16 v[64:79], v[148:151], v[140:143], v[64:79]
	v_mfma_f32_32x32x16_bf16 v[0:15], v[132:135], v[140:143], v[0:15]
	v_mfma_f32_32x32x16_bf16 v[80:95], v[148:151], v[156:159], v[80:95]
	v_mfma_f32_32x32x16_bf16 v[16:31], v[132:135], v[156:159], v[16:31]
	v_mfma_f32_32x32x16_bf16 v[96:111], v[148:151], v[212:215], v[96:111]
	v_mfma_f32_32x32x16_bf16 v[32:47], v[132:135], v[212:215], v[32:47]
	s_waitcnt lgkmcnt(0)
	v_mfma_f32_32x32x16_bf16 v[112:127], v[148:151], v[220:223], v[112:127]
	v_mfma_f32_32x32x16_bf16 v[48:63], v[132:135], v[220:223], v[48:63]
	ds_read_b128 v[128:131], v207 offset:4096
	ds_read_b128 v[132:135], v224
	ds_read_b128 v[136:139], v225 offset:4096
	ds_read_b128 v[140:143], v226
	s_waitcnt lgkmcnt(2)
	v_mfma_f32_32x32x16_bf16 v[144:159], v[128:131], v[132:135], 0
	ds_read_b128 v[128:131], v227 offset:4096
	ds_read_b128 v[132:135], v228
	s_waitcnt lgkmcnt(2)
	v_mfma_f32_32x32x16_bf16 v[144:159], v[136:139], v[140:143], v[144:159]
	ds_read_b128 v[136:139], v230 offset:4096
	ds_read_b128 v[140:143], v232
	s_waitcnt lgkmcnt(2)
	v_mfma_f32_32x32x16_bf16 v[144:159], v[128:131], v[132:135], v[144:159]
	ds_read_b128 v[128:131], v207 offset:12288
	ds_read_b128 v[132:135], v224 offset:4096
	s_waitcnt lgkmcnt(2)
	v_mfma_f32_32x32x16_bf16 v[144:159], v[136:139], v[140:143], v[144:159]
	ds_read_b128 v[208:211], v225 offset:12288
	ds_read_b128 v[212:215], v226 offset:4096
	s_waitcnt lgkmcnt(2)
	v_mfma_f32_32x32x16_bf16 v[128:143], v[128:131], v[132:135], 0
	s_nop 7
	v_exp_f32_e32 v229, v144
	v_exp_f32_e32 v145, v145
	v_exp_f32_e32 v231, v146
	v_exp_f32_e32 v147, v147
	ds_read_b128 v[216:219], v227 offset:12288
	ds_read_b128 v[220:223], v228 offset:4096
	s_waitcnt lgkmcnt(2)
	v_mfma_f32_32x32x16_bf16 v[128:143], v[208:211], v[212:215], v[128:143]
	v_exp_f32_e32 v233, v148
	v_exp_f32_e32 v235, v149
	v_exp_f32_e32 v237, v150
	v_exp_f32_e32 v239, v151
	ds_read_b128 v[148:151], v230 offset:12288
	ds_read_b128 v[208:211], v232 offset:4096
	s_waitcnt lgkmcnt(2)
	v_mfma_f32_32x32x16_bf16 v[128:143], v[216:219], v[220:223], v[128:143]
	v_exp_f32_e32 v241, v152
	v_exp_f32_e32 v243, v153
	v_exp_f32_e32 v245, v154
	v_exp_f32_e32 v247, v155
	s_waitcnt lgkmcnt(0)
	v_mfma_f32_32x32x16_bf16 v[128:143], v[148:151], v[208:211], v[128:143]
	v_exp_f32_e32 v249, v156
	v_exp_f32_e32 v251, v157
	v_exp_f32_e32 v207, v158
	v_exp_f32_e32 v163, v159
	s_nop 7
	v_exp_f32_e32 v228, v128
	v_exp_f32_e32 v146, v129
	v_exp_f32_e32 v230, v130
	v_exp_f32_e32 v144, v131
	v_exp_f32_e32 v232, v132
	v_exp_f32_e32 v238, v133
	v_exp_f32_e32 v236, v134
	v_exp_f32_e32 v234, v135
	v_exp_f32_e32 v240, v136
	v_exp_f32_e32 v246, v137
	v_exp_f32_e32 v244, v138
	v_exp_f32_e32 v242, v139
	v_exp_f32_e32 v248, v140
	v_exp_f32_e32 v162, v141
	v_exp_f32_e32 v206, v142
	v_exp_f32_e32 v250, v143
	v_cvt_pk_bf16_f32 v148, v229, v145
	v_cvt_pk_bf16_f32 v149, v231, v147
	v_cvt_pk_bf16_f32 v150, v233, v235
	v_cvt_pk_bf16_f32 v151, v237, v239
	v_cvt_pk_bf16_f32 v152, v241, v243
	v_cvt_pk_bf16_f32 v153, v245, v247
	v_cvt_pk_bf16_f32 v154, v249, v251
	v_cvt_pk_bf16_f32 v155, v207, v163
	v_cvt_pk_bf16_f32 v128, v228, v146
	v_cvt_pk_bf16_f32 v129, v230, v144
	v_cvt_pk_bf16_f32 v130, v232, v238
	v_cvt_pk_bf16_f32 v131, v236, v234
	v_cvt_pk_bf16_f32 v132, v240, v246
	v_cvt_pk_bf16_f32 v133, v244, v242
	v_cvt_pk_bf16_f32 v134, v248, v162
	v_cvt_pk_bf16_f32 v135, v206, v250
	s_addk_i32 s5, 0x4000
	s_add_i32 s4, s4, 0x10000
	s_and_b32 s7, s5, 0x4000
	ds_read_b64_tr_b16 v[136:137], v160 offset:40960
	ds_read_b64_tr_b16 v[138:139], v160 offset:43008
	ds_read_b64_tr_b16 v[140:141], v160 offset:45056
	ds_read_b64_tr_b16 v[142:143], v160 offset:47104
	ds_read_b64_tr_b16 v[156:157], v252 offset:40960
	ds_read_b64_tr_b16 v[158:159], v252 offset:43008
	ds_read_b64_tr_b16 v[208:209], v252 offset:45056
	ds_read_b64_tr_b16 v[210:211], v252 offset:47104
	ds_read_b64_tr_b16 v[212:213], v203 offset:40960
	ds_read_b64_tr_b16 v[214:215], v203 offset:43008
	ds_read_b64_tr_b16 v[216:217], v203 offset:45056
	ds_read_b64_tr_b16 v[218:219], v203 offset:47104
	ds_read_b64_tr_b16 v[220:221], v205 offset:40960
	ds_read_b64_tr_b16 v[222:223], v205 offset:43008
	ds_read_b64_tr_b16 v[224:225], v205 offset:45056
	ds_read_b64_tr_b16 v[226:227], v205 offset:47104
	s_waitcnt lgkmcnt(14)
	v_mfma_f32_32x32x16_bf16 v[64:79], v[148:151], v[136:139], v[64:79]
	v_mfma_f32_32x32x16_bf16 v[0:15], v[128:131], v[136:139], v[0:15]
	s_waitcnt lgkmcnt(10)
	v_mfma_f32_32x32x16_bf16 v[80:95], v[148:151], v[156:159], v[80:95]
	v_mfma_f32_32x32x16_bf16 v[16:31], v[128:131], v[156:159], v[16:31]
	s_waitcnt lgkmcnt(6)
	v_mfma_f32_32x32x16_bf16 v[96:111], v[148:151], v[212:215], v[96:111]
	v_mfma_f32_32x32x16_bf16 v[32:47], v[128:131], v[212:215], v[32:47]
	s_waitcnt lgkmcnt(2)
	v_mfma_f32_32x32x16_bf16 v[112:127], v[148:151], v[220:223], v[112:127]
	v_mfma_f32_32x32x16_bf16 v[48:63], v[128:131], v[220:223], v[48:63]
	v_add_f32_e64 v128, v172, v176
	v_add_f32_e64 v129, v173, v177
	v_add_f32_e64 v130, v168, v170
	v_add_f32_e64 v131, v169, v171
	v_add_f32_e64 v128, v128, 0
	v_add_f32_e64 v129, v129, 0
	v_pk_add_f32 v[136:137], v[182:183], v[188:189]
	v_pk_add_f32 v[130:131], v[130:131], 0 op_sel_hi:[1,0]
	v_pk_add_f32 v[128:129], v[136:137], v[128:129]
	v_pk_add_f32 v[136:137], v[174:175], v[178:179]
	v_pk_add_f32 v[138:139], v[232:233], v[236:237]
	v_pk_add_f32 v[130:131], v[136:137], v[130:131]
	v_pk_add_f32 v[136:137], v[192:193], v[194:195]
	v_mfma_f32_32x32x16_bf16 v[64:79], v[152:155], v[140:143], v[64:79]
	v_add_f32_e64 v128, v136, v128
	v_add_f32_e64 v129, v137, v129
	v_add_f32_e64 v136, v180, v186
	v_add_f32_e64 v137, v181, v187
	v_add_f32_e64 v130, v136, v130
	v_add_f32_e64 v131, v137, v131
	v_pk_add_f32 v[136:137], v[196:197], v[198:199]
	s_nop 0
	v_pk_add_f32 v[128:129], v[136:137], v[128:129]
	v_pk_add_f32 v[136:137], v[184:185], v[190:191]
	v_mfma_f32_32x32x16_bf16 v[0:15], v[132:135], v[140:143], v[0:15]
	v_add_f32_e64 v130, v136, v130
	v_add_f32_e64 v131, v137, v131
	v_add_f32_e64 v136, v144, v146
	v_add_f32_e64 v137, v145, v147
	v_add_f32_e64 v128, v128, v130
	v_add_f32_e64 v129, v129, v131
	v_pk_add_f32 v[130:131], v[228:229], v[230:231]
	v_pk_add_f32 v[136:137], v[136:137], 0 op_sel_hi:[1,0]
	v_pk_add_f32 v[130:131], v[130:131], 0 op_sel_hi:[1,0]
	v_pk_add_f32 v[128:129], v[166:167], v[128:129]
	v_mfma_f32_32x32x16_bf16 v[80:95], v[152:155], v[208:211], v[80:95]
	v_add_f32_e64 v130, v138, v130
	v_add_f32_e64 v131, v139, v131
	v_add_f32_e64 v138, v234, v238
	v_add_f32_e64 v139, v235, v239
	v_add_f32_e64 v136, v138, v136
	v_add_f32_e64 v137, v139, v137
	v_pk_add_f32 v[138:139], v[240:241], v[244:245]
	s_nop 0
	v_pk_add_f32 v[130:131], v[138:139], v[130:131]
	v_mfma_f32_32x32x16_bf16 v[16:31], v[132:135], v[208:211], v[16:31]
	v_add_f32_e64 v138, v242, v246
	v_add_f32_e64 v139, v243, v247
	v_add_f32_e64 v136, v138, v136
	v_add_f32_e64 v137, v139, v137
	v_add_f32_e64 v138, v248, v206
	v_add_f32_e64 v139, v249, v207
	v_pk_add_f32 v[130:131], v[138:139], v[130:131]
	v_pk_add_f32 v[138:139], v[250:251], v[162:163]
	v_mfma_f32_32x32x16_bf16 v[96:111], v[152:155], v[216:219], v[96:111]
	v_add_f32_e64 v136, v138, v136
	v_add_f32_e64 v137, v139, v137
	v_add_f32_e64 v130, v130, v136
	v_add_f32_e64 v131, v131, v137
	v_add_f32_e64 v166, v128, v130
	v_add_f32_e64 v167, v129, v131
	v_mbcnt_lo_u32_b32 v168, -1, 0
	v_mbcnt_hi_u32_b32 v168, -1, v168
	v_ashrrev_i32_e32 v169, 5, v168
	v_lshlrev_b32_e32 v170, 7, v168
	v_lshrrev_b32_e32 v171, 1, v168
	v_and_b32_e32 v170, 0xf80, v170
	v_bitop3_b32 v172, v171, v169, 7 bitop3:0x6c
	v_lshl_add_u32 v172, v172, 4, v170
	v_add_u32_e32 v173, 2, v169
	v_bitop3_b32 v173, v173, v171, 7 bitop3:0x78
	v_lshl_add_u32 v173, v173, 4, v170
	v_add_u32_e32 v160, s7, v172
	v_add_u32_e32 v203, s48, v172
	v_add_u32_e32 v205, s7, v173
	v_add_u32_e32 v252, s48, v173
	v_mfma_f32_32x32x16_bf16 v[32:47], v[132:135], v[216:219], v[32:47]
	s_waitcnt lgkmcnt(0)
	v_mfma_f32_32x32x16_bf16 v[112:127], v[152:155], v[224:227], v[112:127]
	v_mfma_f32_32x32x16_bf16 v[48:63], v[132:135], v[224:227], v[48:63]
	s_waitcnt vmcnt(0)
	s_cmp_eq_u32 s4, 0x400000
	s_cbranch_scc0 .Lattn_head_a
	s_barrier
